# v70 + nt (streaming) hint on the f32 weight loads of the group-B tail transposes
# baseline (speedup 1.0000x reference)
.LBB0_1121:
	s_waitcnt vmcnt(43)
	v_add_u32_e32 v10, s10, v5
	s_waitcnt vmcnt(41)
	v_add_u32_e32 v14, s6, v5
	s_ashr_i32 s13, s12, 31
	s_ashr_i32 s9, s8, 31
	v_ashrrev_i32_e32 v11, 31, v10
	v_ashrrev_i32_e32 v15, 31, v14
	v_lshl_add_u64 v[12:13], s[12:13], 2, v[2:3]
	s_waitcnt vmcnt(40)
	v_lshl_add_u64 v[16:17], s[8:9], 2, v[2:3]
	v_lshlrev_b64 v[10:11], 15, v[10:11]
	v_lshlrev_b64 v[14:15], 15, v[14:15]
	s_waitcnt vmcnt(31)
	v_lshl_add_u64 v[34:35], v[12:13], 0, v[10:11]
	s_waitcnt vmcnt(29)
	v_lshl_add_u64 v[38:39], v[16:17], 0, v[14:15]
	s_mov_b32 s9, 0x80000
	global_load_dwordx4 v[10:13], v[34:35], off nt
	global_load_dwordx4 v[14:17], v[38:39], off nt
	v_add_co_u32_e32 v18, vcc, s9, v34
	v_add_u32_e32 v0, 0x8100, v8
	s_nop 0
	v_addc_co_u32_e32 v19, vcc, 0, v35, vcc
	global_load_dwordx4 v[18:21], v[18:19], off nt
	v_add_co_u32_e32 v22, vcc, s9, v38
	s_mov_b32 s9, 0x100000
	s_nop 0
	v_addc_co_u32_e32 v23, vcc, 0, v39, vcc
	global_load_dwordx4 v[22:25], v[22:23], off nt
	v_add_co_u32_e32 v26, vcc, s9, v34
	s_add_i32 s7, s7, s2
	s_nop 0
	v_addc_co_u32_e32 v27, vcc, 0, v35, vcc
	global_load_dwordx4 v[26:29], v[26:27], off nt
	v_add_co_u32_e32 v30, vcc, s9, v38
	s_mov_b32 s9, 0x180000
	s_nop 0
	v_addc_co_u32_e32 v31, vcc, 0, v39, vcc
	global_load_dwordx4 v[30:33], v[30:31], off nt
	v_add_co_u32_e32 v34, vcc, s9, v34
	s_ashr_i32 s11, s10, 31
	s_nop 0
	v_addc_co_u32_e32 v35, vcc, 0, v35, vcc
	global_load_dwordx4 v[34:37], v[34:35], off nt
	v_add_co_u32_e32 v38, vcc, s9, v38
	s_nop 1
	v_addc_co_u32_e32 v39, vcc, 0, v39, vcc
	global_load_dwordx4 v[38:41], v[38:39], off nt
	s_and_b64 vcc, exec, s[4:5]
	s_waitcnt vmcnt(7)
	ds_write2_b32 v8, v10, v11 offset1:1
	ds_write2_b32 v8, v12, v13 offset0:2 offset1:3
	s_waitcnt vmcnt(6)
	ds_write2_b32 v0, v14, v15 offset1:1
	v_add_u32_e32 v0, 0x8108, v8
	ds_write2_b32 v0, v16, v17 offset1:1
	v_add_u32_e32 v0, 0x2040, v8
	s_waitcnt vmcnt(5)
	ds_write2_b32 v0, v18, v19 offset1:1
	v_add_u32_e32 v0, 0x2048, v8
	ds_write2_b32 v0, v20, v21 offset1:1
	v_add_u32_e32 v0, 0xa140, v8
	s_waitcnt vmcnt(4)
	ds_write2_b32 v0, v22, v23 offset1:1
	v_add_u32_e32 v0, 0xa148, v8
	ds_write2_b32 v0, v24, v25 offset1:1
	v_add_u32_e32 v0, 0x4080, v8
	s_waitcnt vmcnt(3)
	ds_write2_b32 v0, v26, v27 offset1:1
	v_add_u32_e32 v0, 0x4088, v8
	ds_write2_b32 v0, v28, v29 offset1:1
	v_add_u32_e32 v0, 0xc180, v8
	s_waitcnt vmcnt(2)
	ds_write2_b32 v0, v30, v31 offset1:1
	v_add_u32_e32 v0, 0xc188, v8
	ds_write2_b32 v0, v32, v33 offset1:1
	v_add_u32_e32 v0, 0x60c0, v8
	s_waitcnt vmcnt(1)
	ds_write2_b32 v0, v34, v35 offset1:1
	v_add_u32_e32 v0, 0x60c8, v8
	ds_write2_b32 v0, v36, v37 offset1:1
	v_add_u32_e32 v0, 0xe1c0, v8
	s_waitcnt vmcnt(0)
	ds_write2_b32 v0, v38, v39 offset1:1
	v_add_u32_e32 v0, 0xe1c8, v8
	ds_write2_b32 v0, v40, v41 offset1:1
	s_waitcnt lgkmcnt(0)
	s_barrier
	ds_read2_b32 v[10:11], v7 offset1:129
	v_add_u32_e32 v0, 0x400, v7
	s_waitcnt lgkmcnt(0)
	v_cvt_pk_bf16_f32 v10, v10, v11
	ds_read2_b32 v[12:13], v0 offset0:2 offset1:131
	v_add_u32_e32 v0, 0x800, v7
	s_waitcnt lgkmcnt(0)
	v_cvt_pk_bf16_f32 v11, v12, v13
	ds_read2_b32 v[12:13], v0 offset0:4 offset1:133
	v_add_u32_e32 v0, 0xc00, v7
	s_waitcnt lgkmcnt(0)
	v_cvt_pk_bf16_f32 v12, v12, v13
	ds_read2_b32 v[14:15], v0 offset0:6 offset1:135
	v_add_u32_e32 v0, 0x1000, v7
	s_waitcnt lgkmcnt(0)
	v_cvt_pk_bf16_f32 v13, v14, v15
	ds_read2_b32 v[14:15], v0 offset0:8 offset1:137
	v_add_u32_e32 v0, 0x1400, v7
	s_waitcnt lgkmcnt(0)
	v_cvt_pk_bf16_f32 v14, v14, v15
	ds_read2_b32 v[16:17], v0 offset0:10 offset1:139
	v_add_u32_e32 v0, 0x1800, v7
	s_waitcnt lgkmcnt(0)
	v_cvt_pk_bf16_f32 v15, v16, v17
	ds_read2_b32 v[16:17], v0 offset0:12 offset1:141
	v_add_u32_e32 v0, 0x1c00, v7
	s_waitcnt lgkmcnt(0)
	v_cvt_pk_bf16_f32 v16, v16, v17
	ds_read2_b32 v[18:19], v0 offset0:14 offset1:143
	s_waitcnt lgkmcnt(0)
	v_cvt_pk_bf16_f32 v17, v18, v19
	v_add_u32_e32 v18, s7, v6
	v_ashrrev_i32_e32 v19, 31, v18
	v_lshlrev_b64 v[18:19], 12, v[18:19]
	v_lshl_add_u64 v[18:19], s[0:1], 0, v[18:19]
	v_lshl_add_u64 v[18:19], s[10:11], 1, v[18:19]
	v_lshlrev_b32_e32 v0, 1, v4
	v_lshl_add_u64 v[18:19], v[18:19], 0, v[0:1]
	global_store_dwordx4 v[18:19], v[10:13], off
	global_store_dwordx4 v[18:19], v[14:17], off offset:16
	s_cbranch_vccnz .LBB0_1116
	v_add_u32_e32 v9, 0x8000, v7
	ds_read2_b32 v[10:11], v9 offset0:64 offset1:193
	v_add_u32_e32 v9, 0x8400, v7
	s_waitcnt lgkmcnt(0)
	v_cvt_pk_bf16_f32 v10, v10, v11
	ds_read2_b32 v[12:13], v9 offset0:66 offset1:195
	v_add_u32_e32 v9, 0x8800, v7
	s_waitcnt lgkmcnt(0)
	v_cvt_pk_bf16_f32 v11, v12, v13
	ds_read2_b32 v[12:13], v9 offset0:68 offset1:197
	v_add_u32_e32 v9, 0x8c00, v7
	s_waitcnt lgkmcnt(0)
	v_cvt_pk_bf16_f32 v12, v12, v13
	ds_read2_b32 v[14:15], v9 offset0:70 offset1:199
	v_add_u32_e32 v9, 0x9000, v7
	s_waitcnt lgkmcnt(0)
	v_cvt_pk_bf16_f32 v13, v14, v15
	ds_read2_b32 v[14:15], v9 offset0:72 offset1:201
	v_add_u32_e32 v9, 0x9400, v7
	s_waitcnt lgkmcnt(0)
	v_cvt_pk_bf16_f32 v14, v14, v15
	ds_read2_b32 v[16:17], v9 offset0:74 offset1:203
	v_add_u32_e32 v9, 0x9800, v7
	s_waitcnt lgkmcnt(0)
	v_cvt_pk_bf16_f32 v15, v16, v17
	ds_read2_b32 v[16:17], v9 offset0:76 offset1:205
	v_add_u32_e32 v9, 0x9c00, v7
	s_waitcnt lgkmcnt(0)
	v_cvt_pk_bf16_f32 v16, v16, v17
	ds_read2_b32 v[18:19], v9 offset0:78 offset1:207
	s_waitcnt lgkmcnt(0)
	v_cvt_pk_bf16_f32 v17, v18, v19
	v_add_u32_e32 v18, s8, v6
	v_ashrrev_i32_e32 v19, 31, v18
	v_lshlrev_b64 v[18:19], 12, v[18:19]
	v_lshl_add_u64 v[18:19], s[0:1], 0, v[18:19]
	s_ashr_i32 s7, s6, 31
	v_lshl_add_u64 v[18:19], s[6:7], 1, v[18:19]
	v_lshl_add_u64 v[18:19], v[18:19], 0, v[0:1]
	global_store_dwordx4 v[18:19], v[10:13], off
	global_store_dwordx4 v[18:19], v[14:17], off offset:16
	s_branch .LBB0_1116

.LBB0_1130:
	s_waitcnt vmcnt(43)
	v_add_u32_e32 v10, s10, v5
	s_waitcnt vmcnt(41)
	v_add_u32_e32 v14, s6, v5
	s_ashr_i32 s13, s12, 31
	s_ashr_i32 s9, s8, 31
	v_ashrrev_i32_e32 v11, 31, v10
	v_ashrrev_i32_e32 v15, 31, v14
	v_lshl_add_u64 v[12:13], s[12:13], 2, v[2:3]
	s_waitcnt vmcnt(40)
	v_lshl_add_u64 v[16:17], s[8:9], 2, v[2:3]
	v_lshlrev_b64 v[10:11], 13, v[10:11]
	v_lshlrev_b64 v[14:15], 13, v[14:15]
	s_waitcnt vmcnt(31)
	v_lshl_add_u64 v[34:35], v[12:13], 0, v[10:11]
	s_waitcnt vmcnt(29)
	v_lshl_add_u64 v[38:39], v[16:17], 0, v[14:15]
	s_mov_b32 s9, 0x20000
	global_load_dwordx4 v[10:13], v[34:35], off nt
	global_load_dwordx4 v[14:17], v[38:39], off nt
	v_add_co_u32_e32 v18, vcc, s9, v34
	v_add_u32_e32 v0, 0x8100, v8
	s_nop 0
	v_addc_co_u32_e32 v19, vcc, 0, v35, vcc
	global_load_dwordx4 v[18:21], v[18:19], off nt
	v_add_co_u32_e32 v22, vcc, s9, v38
	s_mov_b32 s9, 0x40000
	s_nop 0
	v_addc_co_u32_e32 v23, vcc, 0, v39, vcc
	global_load_dwordx4 v[22:25], v[22:23], off nt
	v_add_co_u32_e32 v26, vcc, s9, v34
	s_add_i32 s7, s7, s2
	s_nop 0
	v_addc_co_u32_e32 v27, vcc, 0, v35, vcc
	global_load_dwordx4 v[26:29], v[26:27], off nt
	v_add_co_u32_e32 v30, vcc, s9, v38
	s_mov_b32 s9, 0x60000
	s_nop 0
	v_addc_co_u32_e32 v31, vcc, 0, v39, vcc
	global_load_dwordx4 v[30:33], v[30:31], off nt
	v_add_co_u32_e32 v34, vcc, s9, v34
	s_ashr_i32 s11, s10, 31
	s_nop 0
	v_addc_co_u32_e32 v35, vcc, 0, v35, vcc
	global_load_dwordx4 v[34:37], v[34:35], off nt
	v_add_co_u32_e32 v38, vcc, s9, v38
	s_nop 1
	v_addc_co_u32_e32 v39, vcc, 0, v39, vcc
	global_load_dwordx4 v[38:41], v[38:39], off nt
	s_and_b64 vcc, exec, s[4:5]
	s_waitcnt vmcnt(7)
	ds_write2_b32 v8, v10, v11 offset1:1
	ds_write2_b32 v8, v12, v13 offset0:2 offset1:3
	s_waitcnt vmcnt(6)
	ds_write2_b32 v0, v14, v15 offset1:1
	v_add_u32_e32 v0, 0x8108, v8
	ds_write2_b32 v0, v16, v17 offset1:1
	v_add_u32_e32 v0, 0x2040, v8
	s_waitcnt vmcnt(5)
	ds_write2_b32 v0, v18, v19 offset1:1
	v_add_u32_e32 v0, 0x2048, v8
	ds_write2_b32 v0, v20, v21 offset1:1
	v_add_u32_e32 v0, 0xa140, v8
	s_waitcnt vmcnt(4)
	ds_write2_b32 v0, v22, v23 offset1:1
	v_add_u32_e32 v0, 0xa148, v8
	ds_write2_b32 v0, v24, v25 offset1:1
	v_add_u32_e32 v0, 0x4080, v8
	s_waitcnt vmcnt(3)
	ds_write2_b32 v0, v26, v27 offset1:1
	v_add_u32_e32 v0, 0x4088, v8
	ds_write2_b32 v0, v28, v29 offset1:1
	v_add_u32_e32 v0, 0xc180, v8
	s_waitcnt vmcnt(2)
	ds_write2_b32 v0, v30, v31 offset1:1
	v_add_u32_e32 v0, 0xc188, v8
	ds_write2_b32 v0, v32, v33 offset1:1
	v_add_u32_e32 v0, 0x60c0, v8
	s_waitcnt vmcnt(1)
	ds_write2_b32 v0, v34, v35 offset1:1
	v_add_u32_e32 v0, 0x60c8, v8
	ds_write2_b32 v0, v36, v37 offset1:1
	v_add_u32_e32 v0, 0xe1c0, v8
	s_waitcnt vmcnt(0)
	ds_write2_b32 v0, v38, v39 offset1:1
	v_add_u32_e32 v0, 0xe1c8, v8
	ds_write2_b32 v0, v40, v41 offset1:1
	s_waitcnt lgkmcnt(0)
	s_barrier
	ds_read2_b32 v[10:11], v7 offset1:129
	v_add_u32_e32 v0, 0x400, v7
	s_waitcnt lgkmcnt(0)
	v_cvt_pk_bf16_f32 v10, v10, v11
	ds_read2_b32 v[12:13], v0 offset0:2 offset1:131
	v_add_u32_e32 v0, 0x800, v7
	s_waitcnt lgkmcnt(0)
	v_cvt_pk_bf16_f32 v11, v12, v13
	ds_read2_b32 v[12:13], v0 offset0:4 offset1:133
	v_add_u32_e32 v0, 0xc00, v7
	s_waitcnt lgkmcnt(0)
	v_cvt_pk_bf16_f32 v12, v12, v13
	ds_read2_b32 v[14:15], v0 offset0:6 offset1:135
	v_add_u32_e32 v0, 0x1000, v7
	s_waitcnt lgkmcnt(0)
	v_cvt_pk_bf16_f32 v13, v14, v15
	ds_read2_b32 v[14:15], v0 offset0:8 offset1:137
	v_add_u32_e32 v0, 0x1400, v7
	s_waitcnt lgkmcnt(0)
	v_cvt_pk_bf16_f32 v14, v14, v15
	ds_read2_b32 v[16:17], v0 offset0:10 offset1:139
	v_add_u32_e32 v0, 0x1800, v7
	s_waitcnt lgkmcnt(0)
	v_cvt_pk_bf16_f32 v15, v16, v17
	ds_read2_b32 v[16:17], v0 offset0:12 offset1:141
	v_add_u32_e32 v0, 0x1c00, v7
	s_waitcnt lgkmcnt(0)
	v_cvt_pk_bf16_f32 v16, v16, v17
	ds_read2_b32 v[18:19], v0 offset0:14 offset1:143
	s_waitcnt lgkmcnt(0)
	v_cvt_pk_bf16_f32 v17, v18, v19
	v_add_u32_e32 v18, s7, v6
	v_ashrrev_i32_e32 v19, 31, v18
	v_lshlrev_b64 v[18:19], 12, v[18:19]
	v_lshl_add_u64 v[18:19], s[0:1], 0, v[18:19]
	v_lshl_add_u64 v[18:19], s[10:11], 1, v[18:19]
	v_lshlrev_b32_e32 v0, 1, v4
	v_lshl_add_u64 v[18:19], v[18:19], 0, v[0:1]
	global_store_dwordx4 v[18:19], v[10:13], off
	global_store_dwordx4 v[18:19], v[14:17], off offset:16
	s_cbranch_vccnz .LBB0_1125
	v_add_u32_e32 v9, 0x8000, v7
	ds_read2_b32 v[10:11], v9 offset0:64 offset1:193
	v_add_u32_e32 v9, 0x8400, v7
	s_waitcnt lgkmcnt(0)
	v_cvt_pk_bf16_f32 v10, v10, v11
	ds_read2_b32 v[12:13], v9 offset0:66 offset1:195
	v_add_u32_e32 v9, 0x8800, v7
	s_waitcnt lgkmcnt(0)
	v_cvt_pk_bf16_f32 v11, v12, v13
	ds_read2_b32 v[12:13], v9 offset0:68 offset1:197
	v_add_u32_e32 v9, 0x8c00, v7
	s_waitcnt lgkmcnt(0)
	v_cvt_pk_bf16_f32 v12, v12, v13
	ds_read2_b32 v[14:15], v9 offset0:70 offset1:199
	v_add_u32_e32 v9, 0x9000, v7
	s_waitcnt lgkmcnt(0)
	v_cvt_pk_bf16_f32 v13, v14, v15
	ds_read2_b32 v[14:15], v9 offset0:72 offset1:201
	v_add_u32_e32 v9, 0x9400, v7
	s_waitcnt lgkmcnt(0)
	v_cvt_pk_bf16_f32 v14, v14, v15
	ds_read2_b32 v[16:17], v9 offset0:74 offset1:203
	v_add_u32_e32 v9, 0x9800, v7
	s_waitcnt lgkmcnt(0)
	v_cvt_pk_bf16_f32 v15, v16, v17
	ds_read2_b32 v[16:17], v9 offset0:76 offset1:205
	v_add_u32_e32 v9, 0x9c00, v7
	s_waitcnt lgkmcnt(0)
	v_cvt_pk_bf16_f32 v16, v16, v17
	ds_read2_b32 v[18:19], v9 offset0:78 offset1:207
	s_waitcnt lgkmcnt(0)
	v_cvt_pk_bf16_f32 v17, v18, v19
	v_add_u32_e32 v18, s8, v6
	v_ashrrev_i32_e32 v19, 31, v18
	v_lshlrev_b64 v[18:19], 12, v[18:19]
	v_lshl_add_u64 v[18:19], s[0:1], 0, v[18:19]
	s_ashr_i32 s7, s6, 31
	v_lshl_add_u64 v[18:19], s[6:7], 1, v[18:19]
	v_lshl_add_u64 v[18:19], v[18:19], 0, v[0:1]
	global_store_dwordx4 v[18:19], v[10:13], off
	global_store_dwordx4 v[18:19], v[14:17], off offset:16
	s_branch .LBB0_1125

.LBB0_1140:
	s_waitcnt vmcnt(43)
	v_add_u32_e32 v10, s10, v5
	s_waitcnt vmcnt(41)
	v_add_u32_e32 v14, s6, v5
	s_ashr_i32 s13, s12, 31
	s_ashr_i32 s9, s8, 31
	v_ashrrev_i32_e32 v11, 31, v10
	v_ashrrev_i32_e32 v15, 31, v14
	v_lshl_add_u64 v[12:13], s[12:13], 2, v[2:3]
	s_waitcnt vmcnt(40)
	v_lshl_add_u64 v[16:17], s[8:9], 2, v[2:3]
	v_lshlrev_b64 v[10:11], 13, v[10:11]
	v_lshlrev_b64 v[14:15], 13, v[14:15]
	s_waitcnt vmcnt(31)
	v_lshl_add_u64 v[34:35], v[12:13], 0, v[10:11]
	s_waitcnt vmcnt(29)
	v_lshl_add_u64 v[38:39], v[16:17], 0, v[14:15]
	s_mov_b32 s9, 0x20000
	global_load_dwordx4 v[10:13], v[34:35], off nt
	global_load_dwordx4 v[14:17], v[38:39], off nt
	v_add_co_u32_e32 v18, vcc, s9, v34
	v_add_u32_e32 v0, 0x8100, v8
	s_nop 0
	v_addc_co_u32_e32 v19, vcc, 0, v35, vcc
	global_load_dwordx4 v[18:21], v[18:19], off nt
	v_add_co_u32_e32 v22, vcc, s9, v38
	s_mov_b32 s9, 0x40000
	s_nop 0
	v_addc_co_u32_e32 v23, vcc, 0, v39, vcc
	global_load_dwordx4 v[22:25], v[22:23], off nt
	v_add_co_u32_e32 v26, vcc, s9, v34
	s_add_i32 s7, s7, s2
	s_nop 0
	v_addc_co_u32_e32 v27, vcc, 0, v35, vcc
	global_load_dwordx4 v[26:29], v[26:27], off nt
	v_add_co_u32_e32 v30, vcc, s9, v38
	s_mov_b32 s9, 0x60000
	s_nop 0
	v_addc_co_u32_e32 v31, vcc, 0, v39, vcc
	global_load_dwordx4 v[30:33], v[30:31], off nt
	v_add_co_u32_e32 v34, vcc, s9, v34
	s_ashr_i32 s11, s10, 31
	s_nop 0
	v_addc_co_u32_e32 v35, vcc, 0, v35, vcc
	global_load_dwordx4 v[34:37], v[34:35], off nt
	v_add_co_u32_e32 v38, vcc, s9, v38
	s_nop 1
	v_addc_co_u32_e32 v39, vcc, 0, v39, vcc
	global_load_dwordx4 v[38:41], v[38:39], off nt
	s_and_b64 vcc, exec, s[4:5]
	s_waitcnt vmcnt(7)
	ds_write2_b32 v8, v10, v11 offset1:1
	ds_write2_b32 v8, v12, v13 offset0:2 offset1:3
	s_waitcnt vmcnt(6)
	ds_write2_b32 v0, v14, v15 offset1:1
	v_add_u32_e32 v0, 0x8108, v8
	ds_write2_b32 v0, v16, v17 offset1:1
	v_add_u32_e32 v0, 0x2040, v8
	s_waitcnt vmcnt(5)
	ds_write2_b32 v0, v18, v19 offset1:1
	v_add_u32_e32 v0, 0x2048, v8
	ds_write2_b32 v0, v20, v21 offset1:1
	v_add_u32_e32 v0, 0xa140, v8
	s_waitcnt vmcnt(4)
	ds_write2_b32 v0, v22, v23 offset1:1
	v_add_u32_e32 v0, 0xa148, v8
	ds_write2_b32 v0, v24, v25 offset1:1
	v_add_u32_e32 v0, 0x4080, v8
	s_waitcnt vmcnt(3)
	ds_write2_b32 v0, v26, v27 offset1:1
	v_add_u32_e32 v0, 0x4088, v8
	ds_write2_b32 v0, v28, v29 offset1:1
	v_add_u32_e32 v0, 0xc180, v8
	s_waitcnt vmcnt(2)
	ds_write2_b32 v0, v30, v31 offset1:1
	v_add_u32_e32 v0, 0xc188, v8
	ds_write2_b32 v0, v32, v33 offset1:1
	v_add_u32_e32 v0, 0x60c0, v8
	s_waitcnt vmcnt(1)
	ds_write2_b32 v0, v34, v35 offset1:1
	v_add_u32_e32 v0, 0x60c8, v8
	ds_write2_b32 v0, v36, v37 offset1:1
	v_add_u32_e32 v0, 0xe1c0, v8
	s_waitcnt vmcnt(0)
	ds_write2_b32 v0, v38, v39 offset1:1
	v_add_u32_e32 v0, 0xe1c8, v8
	ds_write2_b32 v0, v40, v41 offset1:1
	s_waitcnt lgkmcnt(0)
	s_barrier
	ds_read2_b32 v[10:11], v7 offset1:129
	v_add_u32_e32 v0, 0x400, v7
	s_waitcnt lgkmcnt(0)
	v_cvt_pk_bf16_f32 v10, v10, v11
	ds_read2_b32 v[12:13], v0 offset0:2 offset1:131
	v_add_u32_e32 v0, 0x800, v7
	s_waitcnt lgkmcnt(0)
	v_cvt_pk_bf16_f32 v11, v12, v13
	ds_read2_b32 v[12:13], v0 offset0:4 offset1:133
	v_add_u32_e32 v0, 0xc00, v7
	s_waitcnt lgkmcnt(0)
	v_cvt_pk_bf16_f32 v12, v12, v13
	ds_read2_b32 v[14:15], v0 offset0:6 offset1:135
	v_add_u32_e32 v0, 0x1000, v7
	s_waitcnt lgkmcnt(0)
	v_cvt_pk_bf16_f32 v13, v14, v15
	ds_read2_b32 v[14:15], v0 offset0:8 offset1:137
	v_add_u32_e32 v0, 0x1400, v7
	s_waitcnt lgkmcnt(0)
	v_cvt_pk_bf16_f32 v14, v14, v15
	ds_read2_b32 v[16:17], v0 offset0:10 offset1:139
	v_add_u32_e32 v0, 0x1800, v7
	s_waitcnt lgkmcnt(0)
	v_cvt_pk_bf16_f32 v15, v16, v17
	ds_read2_b32 v[16:17], v0 offset0:12 offset1:141
	v_add_u32_e32 v0, 0x1c00, v7
	s_waitcnt lgkmcnt(0)
	v_cvt_pk_bf16_f32 v16, v16, v17
	ds_read2_b32 v[18:19], v0 offset0:14 offset1:143
	s_waitcnt lgkmcnt(0)
	v_cvt_pk_bf16_f32 v17, v18, v19
	v_add_u32_e32 v18, s7, v6
	v_ashrrev_i32_e32 v19, 31, v18
	v_lshlrev_b64 v[18:19], 13, v[18:19]
	v_lshl_add_u64 v[18:19], s[0:1], 0, v[18:19]
	v_lshl_add_u64 v[18:19], s[10:11], 1, v[18:19]
	v_lshlrev_b32_e32 v0, 1, v4
	v_lshl_add_u64 v[18:19], v[18:19], 0, v[0:1]
	global_store_dwordx4 v[18:19], v[10:13], off
	global_store_dwordx4 v[18:19], v[14:17], off offset:16
	s_cbranch_vccnz .LBB0_1135
	v_add_u32_e32 v9, 0x8000, v7
	ds_read2_b32 v[10:11], v9 offset0:64 offset1:193
	v_add_u32_e32 v9, 0x8400, v7
	s_waitcnt lgkmcnt(0)
	v_cvt_pk_bf16_f32 v10, v10, v11
	ds_read2_b32 v[12:13], v9 offset0:66 offset1:195
	v_add_u32_e32 v9, 0x8800, v7
	s_waitcnt lgkmcnt(0)
	v_cvt_pk_bf16_f32 v11, v12, v13
	ds_read2_b32 v[12:13], v9 offset0:68 offset1:197
	v_add_u32_e32 v9, 0x8c00, v7
	s_waitcnt lgkmcnt(0)
	v_cvt_pk_bf16_f32 v12, v12, v13
	ds_read2_b32 v[14:15], v9 offset0:70 offset1:199
	v_add_u32_e32 v9, 0x9000, v7
	s_waitcnt lgkmcnt(0)
	v_cvt_pk_bf16_f32 v13, v14, v15
	ds_read2_b32 v[14:15], v9 offset0:72 offset1:201
	v_add_u32_e32 v9, 0x9400, v7
	s_waitcnt lgkmcnt(0)
	v_cvt_pk_bf16_f32 v14, v14, v15
	ds_read2_b32 v[16:17], v9 offset0:74 offset1:203
	v_add_u32_e32 v9, 0x9800, v7
	s_waitcnt lgkmcnt(0)
	v_cvt_pk_bf16_f32 v15, v16, v17
	ds_read2_b32 v[16:17], v9 offset0:76 offset1:205
	v_add_u32_e32 v9, 0x9c00, v7
	s_waitcnt lgkmcnt(0)
	v_cvt_pk_bf16_f32 v16, v16, v17
	ds_read2_b32 v[18:19], v9 offset0:78 offset1:207
	s_waitcnt lgkmcnt(0)
	v_cvt_pk_bf16_f32 v17, v18, v19
	v_add_u32_e32 v18, s8, v6
	v_ashrrev_i32_e32 v19, 31, v18
	v_lshlrev_b64 v[18:19], 13, v[18:19]
	v_lshl_add_u64 v[18:19], s[0:1], 0, v[18:19]
	s_ashr_i32 s7, s6, 31
	v_lshl_add_u64 v[18:19], s[6:7], 1, v[18:19]
	v_lshl_add_u64 v[18:19], v[18:19], 0, v[0:1]
	global_store_dwordx4 v[18:19], v[10:13], off
	global_store_dwordx4 v[18:19], v[14:17], off offset:16
	s_branch .LBB0_1135

.LBB0_1149:
	s_ashr_i32 s13, s12, 31
	s_ashr_i32 s9, s8, 31
	v_add_u32_e32 v0, s10, v5
	s_waitcnt vmcnt(31)
	v_lshl_add_u64 v[34:35], s[12:13], 2, v[2:3]
	v_add_u32_e32 v9, s6, v5
	s_waitcnt vmcnt(29)
	v_lshl_add_u64 v[38:39], s[8:9], 2, v[2:3]
	s_mov_b32 s7, 0xc000
	v_mad_i64_i32 v[10:11], s[18:19], v0, s7, v[34:35]
	v_mad_i64_i32 v[14:15], s[18:19], v9, s7, v[38:39]
	global_load_dwordx4 v[10:13], v[10:11], off nt
	v_add_u32_e32 v18, 16, v0
	global_load_dwordx4 v[14:17], v[14:15], off nt
	v_mad_i64_i32 v[18:19], s[18:19], v18, s7, v[34:35]
	global_load_dwordx4 v[18:21], v[18:19], off nt
	v_add_u32_e32 v22, 16, v9
	v_mad_i64_i32 v[22:23], s[18:19], v22, s7, v[38:39]
	global_load_dwordx4 v[22:25], v[22:23], off nt
	v_add_u32_e32 v26, 32, v0
	v_mad_i64_i32 v[26:27], s[18:19], v26, s7, v[34:35]
	global_load_dwordx4 v[26:29], v[26:27], off nt
	v_add_u32_e32 v30, 32, v9
	v_mad_i64_i32 v[30:31], s[18:19], v30, s7, v[38:39]
	global_load_dwordx4 v[30:33], v[30:31], off nt
	v_add_u32_e32 v0, 48, v0
	v_mad_i64_i32 v[34:35], s[18:19], v0, s7, v[34:35]
	global_load_dwordx4 v[34:37], v[34:35], off nt
	v_add_u32_e32 v0, 48, v9
	v_mad_i64_i32 v[38:39], s[18:19], v0, s7, v[38:39]
	global_load_dwordx4 v[38:41], v[38:39], off nt
	v_add_u32_e32 v0, 0x8100, v8
	s_ashr_i32 s11, s10, 31
	s_and_b64 vcc, exec, s[4:5]
	s_waitcnt vmcnt(7)
	ds_write2_b32 v8, v10, v11 offset1:1
	ds_write2_b32 v8, v12, v13 offset0:2 offset1:3
	s_waitcnt vmcnt(6)
	ds_write2_b32 v0, v14, v15 offset1:1
	v_add_u32_e32 v0, 0x8108, v8
	ds_write2_b32 v0, v16, v17 offset1:1
	v_add_u32_e32 v0, 0x2040, v8
	s_waitcnt vmcnt(5)
	ds_write2_b32 v0, v18, v19 offset1:1
	v_add_u32_e32 v0, 0x2048, v8
	ds_write2_b32 v0, v20, v21 offset1:1
	v_add_u32_e32 v0, 0xa140, v8
	s_waitcnt vmcnt(4)
	ds_write2_b32 v0, v22, v23 offset1:1
	v_add_u32_e32 v0, 0xa148, v8
	ds_write2_b32 v0, v24, v25 offset1:1
	v_add_u32_e32 v0, 0x4080, v8
	s_waitcnt vmcnt(3)
	ds_write2_b32 v0, v26, v27 offset1:1
	v_add_u32_e32 v0, 0x4088, v8
	ds_write2_b32 v0, v28, v29 offset1:1
	v_add_u32_e32 v0, 0xc180, v8
	s_waitcnt vmcnt(2)
	ds_write2_b32 v0, v30, v31 offset1:1
	v_add_u32_e32 v0, 0xc188, v8
	ds_write2_b32 v0, v32, v33 offset1:1
	v_add_u32_e32 v0, 0x60c0, v8
	s_waitcnt vmcnt(1)
	ds_write2_b32 v0, v34, v35 offset1:1
	v_add_u32_e32 v0, 0x60c8, v8
	ds_write2_b32 v0, v36, v37 offset1:1
	v_add_u32_e32 v0, 0xe1c0, v8
	s_waitcnt vmcnt(0)
	ds_write2_b32 v0, v38, v39 offset1:1
	v_add_u32_e32 v0, 0xe1c8, v8
	ds_write2_b32 v0, v40, v41 offset1:1
	s_waitcnt lgkmcnt(0)
	s_barrier
	ds_read2_b32 v[10:11], v7 offset1:129
	v_add_u32_e32 v0, 0x400, v7
	s_waitcnt lgkmcnt(0)
	v_cvt_pk_bf16_f32 v10, v10, v11
	ds_read2_b32 v[12:13], v0 offset0:2 offset1:131
	v_add_u32_e32 v0, 0x800, v7
	s_waitcnt lgkmcnt(0)
	v_cvt_pk_bf16_f32 v11, v12, v13
	ds_read2_b32 v[12:13], v0 offset0:4 offset1:133
	v_add_u32_e32 v0, 0xc00, v7
	s_waitcnt lgkmcnt(0)
	v_cvt_pk_bf16_f32 v12, v12, v13
	ds_read2_b32 v[14:15], v0 offset0:6 offset1:135
	v_add_u32_e32 v0, 0x1000, v7
	s_waitcnt lgkmcnt(0)
	v_cvt_pk_bf16_f32 v13, v14, v15
	ds_read2_b32 v[14:15], v0 offset0:8 offset1:137
	v_add_u32_e32 v0, 0x1400, v7
	s_waitcnt lgkmcnt(0)
	v_cvt_pk_bf16_f32 v14, v14, v15
	ds_read2_b32 v[16:17], v0 offset0:10 offset1:139
	v_add_u32_e32 v0, 0x1800, v7
	s_waitcnt lgkmcnt(0)
	v_cvt_pk_bf16_f32 v15, v16, v17
	ds_read2_b32 v[16:17], v0 offset0:12 offset1:141
	v_add_u32_e32 v0, 0x1c00, v7
	s_waitcnt lgkmcnt(0)
	v_cvt_pk_bf16_f32 v16, v16, v17
	ds_read2_b32 v[18:19], v0 offset0:14 offset1:143
	s_waitcnt lgkmcnt(0)
	v_cvt_pk_bf16_f32 v17, v18, v19
	v_add_u32_e32 v18, s12, v6
	v_ashrrev_i32_e32 v19, 31, v18
	v_lshlrev_b64 v[18:19], 12, v[18:19]
	v_lshl_add_u64 v[18:19], s[0:1], 0, v[18:19]
	v_lshl_add_u64 v[18:19], s[10:11], 1, v[18:19]
	v_lshlrev_b32_e32 v0, 1, v4
	v_lshl_add_u64 v[18:19], v[18:19], 0, v[0:1]
	global_store_dwordx4 v[18:19], v[10:13], off
	global_store_dwordx4 v[18:19], v[14:17], off offset:16
	s_cbranch_vccnz .LBB0_1144
	v_add_u32_e32 v9, 0x8000, v7
	ds_read2_b32 v[10:11], v9 offset0:64 offset1:193
	v_add_u32_e32 v9, 0x8400, v7
	s_waitcnt lgkmcnt(0)
	v_cvt_pk_bf16_f32 v10, v10, v11
	ds_read2_b32 v[12:13], v9 offset0:66 offset1:195
	v_add_u32_e32 v9, 0x8800, v7
	s_waitcnt lgkmcnt(0)
	v_cvt_pk_bf16_f32 v11, v12, v13
	ds_read2_b32 v[12:13], v9 offset0:68 offset1:197
	v_add_u32_e32 v9, 0x8c00, v7
	s_waitcnt lgkmcnt(0)
	v_cvt_pk_bf16_f32 v12, v12, v13
	ds_read2_b32 v[14:15], v9 offset0:70 offset1:199
	v_add_u32_e32 v9, 0x9000, v7
	s_waitcnt lgkmcnt(0)
	v_cvt_pk_bf16_f32 v13, v14, v15
	ds_read2_b32 v[14:15], v9 offset0:72 offset1:201
	v_add_u32_e32 v9, 0x9400, v7
	s_waitcnt lgkmcnt(0)
	v_cvt_pk_bf16_f32 v14, v14, v15
	ds_read2_b32 v[16:17], v9 offset0:74 offset1:203
	v_add_u32_e32 v9, 0x9800, v7
	s_waitcnt lgkmcnt(0)
	v_cvt_pk_bf16_f32 v15, v16, v17
	ds_read2_b32 v[16:17], v9 offset0:76 offset1:205
	v_add_u32_e32 v9, 0x9c00, v7
	s_waitcnt lgkmcnt(0)
	v_cvt_pk_bf16_f32 v16, v16, v17
	ds_read2_b32 v[18:19], v9 offset0:78 offset1:207
	s_waitcnt lgkmcnt(0)
	v_cvt_pk_bf16_f32 v17, v18, v19
	v_add_u32_e32 v18, s8, v6
	v_ashrrev_i32_e32 v19, 31, v18
	v_lshlrev_b64 v[18:19], 12, v[18:19]
	v_lshl_add_u64 v[18:19], s[0:1], 0, v[18:19]
	s_ashr_i32 s7, s6, 31
	v_lshl_add_u64 v[18:19], s[6:7], 1, v[18:19]
	v_lshl_add_u64 v[18:19], v[18:19], 0, v[0:1]
	global_store_dwordx4 v[18:19], v[10:13], off
	global_store_dwordx4 v[18:19], v[14:17], off offset:16
	s_branch .LBB0_1144
